# stack21: prep SSD-conv sweep issues its three history-row loads early instead of serially through one register pair (on top of stack20)
# speedup vs baseline: 1.0011x; 1.0011x over previous
; DI float bf2f(unsigned h) { return __uint_as_float(h << 16); }
; DI void prep_unit(const Params& P, int layer, int b, int c, char* lds, int tid) {
;     ...
;         for (int jj = 0; jj < 3; ++jj) {
;             const int co = 256 * jj + 4 * lane;
;             const f32x4 xb = *(const f32x4*)(sb + co), xw0 = *(const f32x4*)(sw + co), xw1 = *(const f32x4*)(sw + 768 + co), xw2 = *(const f32x4*)(sw + 2 * 768 + co), xw3 = *(const f32x4*)(sw + 3 * 768 + co);
;             u32x2 xin[16];
; #pragma unroll
;             for (int li = 0; li < 16; ++li) xin[li] = *(const u32x2*)(PROJ + (size_t)(R0 + l0 + li) * NPROJ + C_XBC + co);
;             const f32x4 h0 = ld4(PROJ + (size_t)(R0 + l0 - ((s0 >= 1) ? 1 : 0)) * NPROJ + C_XBC + co), h1 = ld4(PROJ + (size_t)(R0 + l0 - ((s0 >= 2) ? 2 : 0)) * NPROJ + C_XBC + co), h2 = ld4(PROJ + (size_t)(R0 + l0 - ((s0 >= 3) ? 3 : 0)) * NPROJ + C_XBC + co);
;             f32x4 xh0 = (s0 >= 1) ? h0 : z4, xh1 = (s0 >= 2) ? h1 : z4, xh2 = (s0 >= 3) ? h2 : z4;
; #pragma unroll
;             for (int li = 0; li < 16; ++li) { const int R = R0 + l0 + li;
;                 const f32x4 x0 = (f32x4){bf2f(xin[li].x & 0xffffu), bf2f(xin[li].x >> 16), bf2f(xin[li].y & 0xffffu), bf2f(xin[li].y >> 16)};
;                 f32x4 y = xw0 * xh2 + xw1 * xh1 + xw2 * xh0 + xw3 * x0 + xb;
;                 xh2 = xh1; xh1 = xh0; xh0 = x0;
.LBB0_193:
	v_lshl_add_u64 v[18:19], s[88:89], 0, v[96:97]
	v_add_co_u32_e32 v14, vcc, 0x1000, v18
	v_lshl_add_u64 v[2:3], s[90:91], 0, v[96:97]
	s_nop 0
	v_addc_co_u32_e32 v15, vcc, 0, v19, vcc
	global_load_dwordx4 v[2:5], v[2:3], off
	s_nop 0
	global_load_dwordx4 v[6:9], v[18:19], off
	global_load_dwordx4 v[10:13], v[18:19], off offset:3072
	v_add_co_u32_e32 v18, vcc, 0x2000, v18
	v_lshl_add_u64 v[98:99], v[92:93], 0, s[38:39]
	s_nop 0
	v_addc_co_u32_e32 v19, vcc, 0, v19, vcc
	v_add_co_u32_e32 v100, vcc, 0x6a00000, v98
	v_lshl_add_u64 v[130:131], v[90:91], 0, s[38:39]
	s_nop 0
	v_addc_co_u32_e32 v101, vcc, 0, v99, vcc
	global_load_dwordx2 v[116:117], v[100:101], off offset:2880
	v_add_co_u32_e32 v100, vcc, 0x6a01000, v98
	global_load_dwordx2 v[130:131], v[130:131], off
	v_lshl_add_u64 v[224:225], v[88:89], 0, s[38:39]
	global_load_dwordx2 v[224:225], v[224:225], off
	v_lshl_add_u64 v[226:227], v[86:87], 0, s[38:39]
	global_load_dwordx2 v[226:227], v[226:227], off
	s_nop 0
	v_addc_co_u32_e32 v101, vcc, 0, v99, vcc
	global_load_dwordx2 v[128:129], v[100:101], off offset:3392
	v_add_co_u32_e32 v100, vcc, 0x6a02000, v98
	global_load_dwordx4 v[14:17], v[14:15], off offset:2048
	s_nop 0
	v_addc_co_u32_e32 v101, vcc, 0, v99, vcc
	global_load_dwordx2 v[126:127], v[100:101], off offset:3904
	v_add_co_u32_e32 v100, vcc, 0x6a04000, v98
	global_load_dwordx4 v[18:21], v[18:19], off offset:1024
	s_nop 0
	v_addc_co_u32_e32 v101, vcc, 0, v99, vcc
	global_load_dwordx2 v[124:125], v[100:101], off offset:320
	v_add_co_u32_e32 v100, vcc, 0x6a05000, v98
	s_mov_b32 s2, 0x1ba00000
	s_nop 0
	v_addc_co_u32_e32 v101, vcc, 0, v99, vcc
	global_load_dwordx2 v[122:123], v[100:101], off offset:832
	v_add_co_u32_e32 v100, vcc, 0x6a06000, v98
	s_mov_b64 s[4:5], 0x400
	s_nop 0
	v_addc_co_u32_e32 v101, vcc, 0, v99, vcc
	global_load_dwordx2 v[120:121], v[100:101], off offset:1344
	v_add_co_u32_e32 v100, vcc, 0x6a07000, v98
	v_lshl_add_u64 v[96:97], v[96:97], 0, s[4:5]
	s_nop 0
	v_addc_co_u32_e32 v101, vcc, 0, v99, vcc
	global_load_dwordx2 v[118:119], v[100:101], off offset:1856
	v_add_co_u32_e32 v100, vcc, 0x6a08000, v98
	v_addc_co_u32_e32 v101, vcc, 0, v99, vcc
	global_load_dwordx2 v[114:115], v[100:101], off offset:2368
	v_add_co_u32_e32 v100, vcc, 0x6a09000, v98
	s_nop 0
	v_addc_co_u32_e32 v101, vcc, 0, v99, vcc
	global_load_dwordx2 v[112:113], v[100:101], off offset:2880
	v_add_co_u32_e32 v100, vcc, 0x6a0a000, v98
	s_nop 0
	v_addc_co_u32_e32 v101, vcc, 0, v99, vcc
	global_load_dwordx2 v[110:111], v[100:101], off offset:3392
	v_add_co_u32_e32 v100, vcc, 0x6a0b000, v98
	s_nop 0
	v_addc_co_u32_e32 v101, vcc, 0, v99, vcc
	global_load_dwordx2 v[108:109], v[100:101], off offset:3904
	v_add_co_u32_e32 v100, vcc, 0x6a0d000, v98
	s_nop 0
	v_addc_co_u32_e32 v101, vcc, 0, v99, vcc
	global_load_dwordx2 v[106:107], v[100:101], off offset:320
	v_add_co_u32_e32 v100, vcc, 0x6a0e000, v98
	s_nop 0
	v_addc_co_u32_e32 v101, vcc, 0, v99, vcc
	global_load_dwordx2 v[104:105], v[100:101], off offset:832
	s_waitcnt vmcnt(16)
	v_lshlrev_b32_e32 v132, 16, v130
	v_and_b32_e32 v133, 0xffff0000, v130
	v_lshlrev_b32_e32 v136, 16, v131
	v_and_b32_e32 v137, 0xffff0000, v131
	v_cndmask_b32_e64 v135, v133, 0, s[56:57]
	v_cndmask_b32_e64 v134, v132, 0, s[56:57]
	v_lshlrev_b32_e32 v132, 16, v117
	v_and_b32_e32 v133, 0xffff0000, v117
	v_cndmask_b32_e64 v137, v137, 0, s[56:57]
	v_cndmask_b32_e64 v136, v136, 0, s[56:57]
	s_waitcnt vmcnt(15)
	v_mov_b64_e32 v[130:131], v[224:225]
	v_lshlrev_b32_e32 v140, 16, v130
	v_and_b32_e32 v141, 0xffff0000, v130
	v_lshlrev_b32_e32 v138, 16, v131
	v_and_b32_e32 v139, 0xffff0000, v131
	s_waitcnt vmcnt(14)
	v_mov_b64_e32 v[130:131], v[226:227]
	v_cndmask_b32_e64 v141, 0, v141, s[58:59]
	v_cndmask_b32_e64 v140, 0, v140, s[58:59]
	v_cndmask_b32_e64 v139, 0, v139, s[58:59]
	v_cndmask_b32_e64 v138, 0, v138, s[58:59]
	v_add_co_u32_e32 v100, vcc, 0x6a0f000, v98
	s_waitcnt vmcnt(0)
	v_lshlrev_b32_e32 v142, 16, v130
	v_and_b32_e32 v130, 0xffff0000, v130
	v_cndmask_b32_e64 v143, 0, v130, s[60:61]
	v_cndmask_b32_e64 v142, 0, v142, s[60:61]
	v_pk_mul_f32 v[142:143], v[6:7], v[142:143]
	v_lshlrev_b32_e32 v144, 16, v131
	v_and_b32_e32 v131, 0xffff0000, v131
	v_pk_fma_f32 v[142:143], v[10:11], v[140:141], v[142:143]
	v_cndmask_b32_e64 v145, 0, v131, s[60:61]
	v_lshlrev_b32_e32 v130, 16, v116
	v_and_b32_e32 v131, 0xffff0000, v116
	v_pk_fma_f32 v[142:143], v[14:15], v[134:135], v[142:143]
	v_cndmask_b32_e64 v144, 0, v144, s[60:61]
	v_pk_fma_f32 v[142:143], v[18:19], v[130:131], v[142:143]
	v_pk_mul_f32 v[116:117], v[8:9], v[144:145]
	v_pk_add_f32 v[142:143], v[2:3], v[142:143]
	v_pk_fma_f32 v[116:117], v[12:13], v[138:139], v[116:117]
	v_mul_f32_e32 v144, 0xbfb8aa3b, v142
	v_exp_f32_e32 v144, v144
	v_pk_fma_f32 v[116:117], v[16:17], v[136:137], v[116:117]
	v_addc_co_u32_e32 v101, vcc, 0, v99, vcc
	v_add_f32_e32 v144, 1.0, v144
	v_rcp_f32_e32 v144, v144
	v_pk_fma_f32 v[116:117], v[20:21], v[132:133], v[116:117]
	global_load_dwordx2 v[102:103], v[100:101], off offset:1344
	v_pk_add_f32 v[116:117], v[4:5], v[116:117]
	v_mul_f32_e32 v142, v142, v144
	v_mul_f32_e32 v144, 0xbfb8aa3b, v143
	v_exp_f32_e32 v144, v144
	v_add_co_u32_e32 v100, vcc, 0x6a10000, v98
	v_pk_mul_f32 v[140:141], v[6:7], v[140:141]
	v_add_f32_e32 v144, 1.0, v144
	v_rcp_f32_e32 v144, v144
	v_addc_co_u32_e32 v101, vcc, 0, v99, vcc
	v_add_co_u32_e32 v98, vcc, 0x6a11000, v98
	v_mul_f32_e32 v143, v143, v144
	v_mul_f32_e32 v144, 0xbfb8aa3b, v116
	v_exp_f32_e32 v144, v144
	v_addc_co_u32_e32 v99, vcc, 0, v99, vcc
	global_load_dwordx2 v[100:101], v[100:101], off offset:1856
	v_add_f32_e32 v144, 1.0, v144
	v_rcp_f32_e32 v144, v144
; DI float bf2f(unsigned h) { return __uint_as_float(h << 16); }
; DI unsigned pk2(float lo, float hi) { return pg8::cvt_pk_bf16(lo, hi); }
; DI float siluf(float v) { return v * __builtin_amdgcn_rcpf(1.f + __expf(-v)); }
; DI void prep_unit(const Params& P, int layer, int b, int c, char* lds, int tid) {
;     ...
; #pragma unroll
;             for (int li = 0; li < 16; ++li) { const int R = R0 + l0 + li;
;                 const f32x4 x0 = (f32x4){bf2f(xin[li].x & 0xffffu), bf2f(xin[li].x >> 16), bf2f(xin[li].y & 0xffffu), bf2f(xin[li].y >> 16)};
;                 f32x4 y = xw0 * xh2 + xw1 * xh1 + xw2 * xh0 + xw3 * x0 + xb;
;                 xh2 = xh1; xh1 = xh0; xh0 = x0;
;                 y.x = siluf(y.x); y.y = siluf(y.y); y.z = siluf(y.z); y.w = siluf(y.w);
;                 u32x2 w; w.x = pk2(y.x, y.y); w.y = pk2(y.z, y.w); *(u32x2*)(SSDB + (size_t)R * 768 + co) = w; }
;         }
	global_load_dwordx2 v[98:99], v[98:99], off offset:2368
	v_cvt_pk_bf16_f32 v142, v142, v143
	v_pk_fma_f32 v[140:141], v[10:11], v[134:135], v[140:141]
	v_mul_f32_e32 v116, v116, v144
	v_mul_f32_e32 v144, 0xbfb8aa3b, v117
	v_exp_f32_e32 v144, v144
	v_pk_fma_f32 v[140:141], v[14:15], v[130:131], v[140:141]
	v_pk_mul_f32 v[138:139], v[8:9], v[138:139]
	v_pk_mul_f32 v[134:135], v[6:7], v[134:135]
	v_add_f32_e32 v144, 1.0, v144
	v_rcp_f32_e32 v144, v144
	v_pk_fma_f32 v[138:139], v[12:13], v[136:137], v[138:139]
	v_pk_fma_f32 v[134:135], v[10:11], v[130:131], v[134:135]
	v_pk_fma_f32 v[138:139], v[16:17], v[132:133], v[138:139]
	v_mul_f32_e32 v117, v117, v144
	v_cvt_pk_bf16_f32 v143, v116, v117
	v_lshl_add_u64 v[116:117], v[94:95], 0, s[38:39]
	v_add_co_u32_e32 v144, vcc, s2, v116
	v_pk_mul_f32 v[136:137], v[8:9], v[136:137]
	s_nop 0
	v_addc_co_u32_e32 v145, vcc, 0, v117, vcc
	global_store_dwordx2 v[144:145], v[142:143], off
	v_lshlrev_b32_e32 v142, 16, v128
	v_and_b32_e32 v143, 0xffff0000, v128
	v_pk_fma_f32 v[140:141], v[18:19], v[142:143], v[140:141]
	v_lshlrev_b32_e32 v128, 16, v129
	v_pk_add_f32 v[140:141], v[2:3], v[140:141]
	v_and_b32_e32 v129, 0xffff0000, v129
	v_mul_f32_e32 v146, 0xbfb8aa3b, v140
	v_exp_f32_e32 v146, v146
	v_pk_fma_f32 v[138:139], v[20:21], v[128:129], v[138:139]
	v_pk_fma_f32 v[134:135], v[14:15], v[142:143], v[134:135]
	v_pk_add_f32 v[138:139], v[4:5], v[138:139]
	v_add_f32_e32 v146, 1.0, v146
	v_rcp_f32_e32 v146, v146
	v_pk_fma_f32 v[136:137], v[12:13], v[132:133], v[136:137]
	s_mov_b32 s2, 0x1ba01000
	v_pk_fma_f32 v[136:137], v[16:17], v[128:129], v[136:137]
	v_mul_f32_e32 v140, v140, v146
	v_mul_f32_e32 v146, 0xbfb8aa3b, v141
	v_exp_f32_e32 v146, v146
	s_add_u32 s38, s38, 0x200
	s_addc_u32 s39, s39, 0
	s_cmpk_eq_i32 s38, 0x600
	v_add_f32_e32 v146, 1.0, v146
	v_rcp_f32_e32 v146, v146
	s_nop 0
	v_mul_f32_e32 v141, v141, v146
	v_mul_f32_e32 v146, 0xbfb8aa3b, v138
	v_exp_f32_e32 v146, v146
	s_nop 0
	v_add_f32_e32 v146, 1.0, v146
	v_rcp_f32_e32 v146, v146
	s_nop 0
	v_mul_f32_e32 v146, v138, v146
	v_mul_f32_e32 v138, 0xbfb8aa3b, v139
	v_exp_f32_e32 v138, v138
	s_nop 0
	v_add_f32_e32 v138, 1.0, v138
	v_rcp_f32_e32 v138, v138
	s_nop 0
	v_mul_f32_e32 v139, v139, v138
	v_cvt_pk_bf16_f32 v138, v140, v141
	v_cvt_pk_bf16_f32 v139, v146, v139
	global_store_dwordx2 v[144:145], v[138:139], off offset:1536
	v_lshlrev_b32_e32 v138, 16, v126
	v_and_b32_e32 v139, 0xffff0000, v126
	v_pk_fma_f32 v[134:135], v[18:19], v[138:139], v[134:135]
	v_lshlrev_b32_e32 v126, 16, v127
	v_pk_add_f32 v[134:135], v[2:3], v[134:135]
	v_and_b32_e32 v127, 0xffff0000, v127
	v_mul_f32_e32 v140, 0xbfb8aa3b, v134
	v_exp_f32_e32 v140, v140
	v_pk_fma_f32 v[136:137], v[20:21], v[126:127], v[136:137]
	v_add_f32_e32 v140, 1.0, v140
	v_rcp_f32_e32 v140, v140
	v_pk_add_f32 v[136:137], v[4:5], v[136:137]
	v_mul_f32_e32 v134, v134, v140
	v_mul_f32_e32 v140, 0xbfb8aa3b, v135
	v_exp_f32_e32 v140, v140
	s_nop 0
	v_add_f32_e32 v140, 1.0, v140
	v_rcp_f32_e32 v140, v140
	s_nop 0
	v_mul_f32_e32 v135, v135, v140
	v_mul_f32_e32 v140, 0xbfb8aa3b, v136
	v_exp_f32_e32 v140, v140
	v_cvt_pk_bf16_f32 v134, v134, v135
	s_nop 0
	v_add_f32_e32 v140, 1.0, v140
	v_rcp_f32_e32 v140, v140
	s_nop 0
	v_mul_f32_e32 v136, v136, v140
	v_mul_f32_e32 v140, 0xbfb8aa3b, v137
	v_exp_f32_e32 v140, v140
	s_nop 0
	v_add_f32_e32 v140, 1.0, v140
	v_rcp_f32_e32 v140, v140
	s_nop 0
	v_mul_f32_e32 v137, v137, v140
	v_pk_mul_f32 v[140:141], v[10:11], v[142:143]
	v_cvt_pk_bf16_f32 v135, v136, v137
	global_store_dwordx2 v[144:145], v[134:135], off offset:3072
	v_pk_fma_f32 v[130:131], v[6:7], v[130:131], v[140:141]
	v_lshlrev_b32_e32 v134, 16, v124
	v_and_b32_e32 v135, 0xffff0000, v124
	v_pk_fma_f32 v[130:131], v[14:15], v[138:139], v[130:131]
	v_pk_mul_f32 v[136:137], v[12:13], v[128:129]
	v_pk_fma_f32 v[130:131], v[18:19], v[134:135], v[130:131]
	v_pk_fma_f32 v[132:133], v[8:9], v[132:133], v[136:137]
	v_pk_add_f32 v[130:131], v[2:3], v[130:131]
	v_lshlrev_b32_e32 v124, 16, v125
	v_mul_f32_e32 v136, 0xbfb8aa3b, v130
	v_exp_f32_e32 v136, v136
	v_and_b32_e32 v125, 0xffff0000, v125
	v_pk_fma_f32 v[132:133], v[16:17], v[126:127], v[132:133]
	v_pk_mul_f32 v[140:141], v[10:11], v[138:139]
	v_add_f32_e32 v136, 1.0, v136
	v_rcp_f32_e32 v136, v136
	v_pk_fma_f32 v[132:133], v[20:21], v[124:125], v[132:133]
	v_pk_fma_f32 v[140:141], v[6:7], v[142:143], v[140:141]
	v_pk_add_f32 v[132:133], v[4:5], v[132:133]
	v_mul_f32_e32 v130, v130, v136
	v_mul_f32_e32 v136, 0xbfb8aa3b, v131
	v_exp_f32_e32 v136, v136
	s_nop 0
	v_add_f32_e32 v136, 1.0, v136
	v_rcp_f32_e32 v136, v136
	s_nop 0
	v_mul_f32_e32 v131, v131, v136
	v_mul_f32_e32 v136, 0xbfb8aa3b, v132
	v_exp_f32_e32 v136, v136
	v_cvt_pk_bf16_f32 v130, v130, v131
	s_nop 0
	v_add_f32_e32 v136, 1.0, v136
	v_rcp_f32_e32 v136, v136
	s_nop 0
	v_mul_f32_e32 v132, v132, v136
	v_mul_f32_e32 v136, 0xbfb8aa3b, v133
	v_exp_f32_e32 v136, v136
	s_nop 0
	v_add_f32_e32 v136, 1.0, v136
	v_rcp_f32_e32 v136, v136
	s_nop 0
	v_mul_f32_e32 v133, v133, v136
	v_cvt_pk_bf16_f32 v131, v132, v133
	v_add_co_u32_e32 v132, vcc, s2, v116
	v_pk_mul_f32 v[136:137], v[12:13], v[126:127]
	s_nop 0
	v_addc_co_u32_e32 v133, vcc, 0, v117, vcc
	global_store_dwordx2 v[132:133], v[130:131], off offset:512
	v_lshlrev_b32_e32 v130, 16, v122
	v_and_b32_e32 v131, 0xffff0000, v122
	v_pk_fma_f32 v[128:129], v[8:9], v[128:129], v[136:137]
	v_pk_fma_f32 v[136:137], v[14:15], v[134:135], v[140:141]
	v_lshlrev_b32_e32 v122, 16, v123
	v_pk_fma_f32 v[136:137], v[18:19], v[130:131], v[136:137]
	v_and_b32_e32 v123, 0xffff0000, v123
	v_pk_add_f32 v[136:137], v[2:3], v[136:137]
	v_pk_fma_f32 v[128:129], v[16:17], v[124:125], v[128:129]
; DI float bf2f(unsigned h) { return __uint_as_float(h << 16); }
; DI unsigned pk2(float lo, float hi) { return pg8::cvt_pk_bf16(lo, hi); }
; DI float siluf(float v) { return v * __builtin_amdgcn_rcpf(1.f + __expf(-v)); }
; DI void prep_unit(const Params& P, int layer, int b, int c, char* lds, int tid) {
;     ...
; #pragma unroll
;             for (int li = 0; li < 16; ++li) { const int R = R0 + l0 + li;
;                 const f32x4 x0 = (f32x4){bf2f(xin[li].x & 0xffffu), bf2f(xin[li].x >> 16), bf2f(xin[li].y & 0xffffu), bf2f(xin[li].y >> 16)};
;                 f32x4 y = xw0 * xh2 + xw1 * xh1 + xw2 * xh0 + xw3 * x0 + xb;
;                 xh2 = xh1; xh1 = xh0; xh0 = x0;
;                 y.x = siluf(y.x); y.y = siluf(y.y); y.z = siluf(y.z); y.w = siluf(y.w);
;                 u32x2 w; w.x = pk2(y.x, y.y); w.y = pk2(y.z, y.w); *(u32x2*)(SSDB + (size_t)R * 768 + co) = w; }
	v_mul_f32_e32 v140, 0xbfb8aa3b, v136
	v_exp_f32_e32 v140, v140
	v_pk_fma_f32 v[128:129], v[20:21], v[122:123], v[128:129]
	s_mov_b32 s2, 0x1ba02000
	v_pk_add_f32 v[128:129], v[4:5], v[128:129]
	v_add_f32_e32 v140, 1.0, v140
	v_rcp_f32_e32 v140, v140
	s_nop 0
	v_mul_f32_e32 v136, v136, v140
	v_mul_f32_e32 v140, 0xbfb8aa3b, v137
	v_exp_f32_e32 v140, v140
	s_nop 0
	v_add_f32_e32 v140, 1.0, v140
	v_rcp_f32_e32 v140, v140
	s_nop 0
	v_mul_f32_e32 v137, v137, v140
	v_mul_f32_e32 v140, 0xbfb8aa3b, v128
	v_exp_f32_e32 v140, v140
	s_nop 0
	v_add_f32_e32 v140, 1.0, v140
	v_rcp_f32_e32 v140, v140
	s_nop 0
	v_mul_f32_e32 v140, v128, v140
	v_mul_f32_e32 v128, 0xbfb8aa3b, v129
	v_exp_f32_e32 v128, v128
	s_nop 0
	v_add_f32_e32 v128, 1.0, v128
	v_rcp_f32_e32 v128, v128
	s_nop 0
	v_mul_f32_e32 v129, v129, v128
	v_cvt_pk_bf16_f32 v128, v136, v137
	v_cvt_pk_bf16_f32 v129, v140, v129
	v_pk_mul_f32 v[140:141], v[10:11], v[134:135]
	global_store_dwordx2 v[132:133], v[128:129], off offset:2048
	v_lshlrev_b32_e32 v128, 16, v120
	v_and_b32_e32 v129, 0xffff0000, v120
	v_lshlrev_b32_e32 v136, 16, v121
	v_and_b32_e32 v137, 0xffff0000, v121
	v_pk_mul_f32 v[120:121], v[12:13], v[124:125]
	v_pk_fma_f32 v[138:139], v[6:7], v[138:139], v[140:141]
	v_pk_fma_f32 v[120:121], v[8:9], v[126:127], v[120:121]
	v_pk_fma_f32 v[126:127], v[14:15], v[130:131], v[138:139]
	v_pk_fma_f32 v[120:121], v[16:17], v[122:123], v[120:121]
	v_pk_fma_f32 v[126:127], v[18:19], v[128:129], v[126:127]
	v_pk_fma_f32 v[120:121], v[20:21], v[136:137], v[120:121]
	v_pk_add_f32 v[126:127], v[2:3], v[126:127]
	v_pk_add_f32 v[120:121], v[4:5], v[120:121]
	v_mul_f32_e32 v138, 0xbfb8aa3b, v126
	v_exp_f32_e32 v138, v138
	s_nop 0
	v_add_f32_e32 v138, 1.0, v138
	v_rcp_f32_e32 v138, v138
	s_nop 0
	v_mul_f32_e32 v126, v126, v138
	v_mul_f32_e32 v138, 0xbfb8aa3b, v127
	v_exp_f32_e32 v138, v138
	s_nop 0
	v_add_f32_e32 v138, 1.0, v138
	v_rcp_f32_e32 v138, v138
	s_nop 0
	v_mul_f32_e32 v127, v127, v138
	v_mul_f32_e32 v138, 0xbfb8aa3b, v120
	v_exp_f32_e32 v138, v138
	s_nop 0
	v_add_f32_e32 v138, 1.0, v138
	v_rcp_f32_e32 v138, v138
	s_nop 0
	v_mul_f32_e32 v138, v120, v138
	v_mul_f32_e32 v120, 0xbfb8aa3b, v121
	v_exp_f32_e32 v120, v120
	s_nop 0
	v_add_f32_e32 v120, 1.0, v120
	v_rcp_f32_e32 v120, v120
	s_nop 0
	v_mul_f32_e32 v121, v121, v120
	v_cvt_pk_bf16_f32 v120, v126, v127
	v_cvt_pk_bf16_f32 v121, v138, v121
	global_store_dwordx2 v[132:133], v[120:121], off offset:3584
	v_pk_mul_f32 v[132:133], v[10:11], v[130:131]
	v_pk_mul_f32 v[126:127], v[12:13], v[122:123]
	v_pk_fma_f32 v[132:133], v[6:7], v[134:135], v[132:133]
	v_lshlrev_b32_e32 v120, 16, v118
	v_and_b32_e32 v121, 0xffff0000, v118
	v_pk_fma_f32 v[124:125], v[8:9], v[124:125], v[126:127]
	v_pk_fma_f32 v[126:127], v[14:15], v[128:129], v[132:133]
	v_lshlrev_b32_e32 v118, 16, v119
	v_pk_fma_f32 v[126:127], v[18:19], v[120:121], v[126:127]
	v_and_b32_e32 v119, 0xffff0000, v119
	v_pk_add_f32 v[126:127], v[2:3], v[126:127]
	v_pk_fma_f32 v[124:125], v[16:17], v[136:137], v[124:125]
	v_mul_f32_e32 v132, 0xbfb8aa3b, v126
	v_exp_f32_e32 v132, v132
	v_pk_fma_f32 v[124:125], v[20:21], v[118:119], v[124:125]
	v_pk_mul_f32 v[134:135], v[10:11], v[128:129]
	v_pk_add_f32 v[124:125], v[4:5], v[124:125]
	v_add_f32_e32 v132, 1.0, v132
	v_rcp_f32_e32 v132, v132
	v_pk_fma_f32 v[130:131], v[6:7], v[130:131], v[134:135]
	v_mul_f32_e32 v126, v126, v132
	v_mul_f32_e32 v132, 0xbfb8aa3b, v127
	v_exp_f32_e32 v132, v132
	v_pk_fma_f32 v[130:131], v[14:15], v[120:121], v[130:131]
	v_add_f32_e32 v132, 1.0, v132
	v_rcp_f32_e32 v132, v132
	s_nop 0
	v_mul_f32_e32 v127, v127, v132
	v_mul_f32_e32 v132, 0xbfb8aa3b, v124
	v_exp_f32_e32 v132, v132
	s_nop 0
	v_add_f32_e32 v132, 1.0, v132
	v_rcp_f32_e32 v132, v132
	s_nop 0
	v_mul_f32_e32 v132, v124, v132
	v_mul_f32_e32 v124, 0xbfb8aa3b, v125
	v_exp_f32_e32 v124, v124
	s_nop 0
	v_add_f32_e32 v124, 1.0, v124
	v_rcp_f32_e32 v124, v124
	s_nop 0
	v_mul_f32_e32 v125, v125, v124
	v_cvt_pk_bf16_f32 v124, v126, v127
	v_add_co_u32_e32 v126, vcc, s2, v116
	v_cvt_pk_bf16_f32 v125, v132, v125
	v_pk_mul_f32 v[132:133], v[12:13], v[136:137]
	s_nop 0
	v_addc_co_u32_e32 v127, vcc, 0, v117, vcc
	global_store_dwordx2 v[126:127], v[124:125], off offset:1024
	v_lshlrev_b32_e32 v124, 16, v114
	v_and_b32_e32 v125, 0xffff0000, v114
	v_pk_fma_f32 v[130:131], v[18:19], v[124:125], v[130:131]
	v_pk_fma_f32 v[122:123], v[8:9], v[122:123], v[132:133]
	v_pk_add_f32 v[130:131], v[2:3], v[130:131]
	v_lshlrev_b32_e32 v114, 16, v115
	v_mul_f32_e32 v132, 0xbfb8aa3b, v130
	v_exp_f32_e32 v132, v132
	v_and_b32_e32 v115, 0xffff0000, v115
	v_pk_fma_f32 v[122:123], v[16:17], v[118:119], v[122:123]
	s_mov_b32 s2, 0x1ba03000
	v_add_f32_e32 v132, 1.0, v132
	v_rcp_f32_e32 v132, v132
	v_pk_fma_f32 v[122:123], v[20:21], v[114:115], v[122:123]
	v_mul_f32_e32 v130, v130, v132
	v_mul_f32_e32 v132, 0xbfb8aa3b, v131
	v_exp_f32_e32 v132, v132
	v_pk_add_f32 v[122:123], v[4:5], v[122:123]
	v_add_f32_e32 v132, 1.0, v132
	v_rcp_f32_e32 v132, v132
	s_nop 0
	v_mul_f32_e32 v131, v131, v132
	v_mul_f32_e32 v132, 0xbfb8aa3b, v122
	v_exp_f32_e32 v132, v132
	s_nop 0
	v_add_f32_e32 v132, 1.0, v132
	v_rcp_f32_e32 v132, v132
	s_nop 0
	v_mul_f32_e32 v132, v122, v132
	v_mul_f32_e32 v122, 0xbfb8aa3b, v123
	v_exp_f32_e32 v122, v122
	s_nop 0
	v_add_f32_e32 v122, 1.0, v122
	v_rcp_f32_e32 v122, v122
	s_nop 0
	v_mul_f32_e32 v123, v123, v122
	v_cvt_pk_bf16_f32 v122, v130, v131
	v_pk_mul_f32 v[130:131], v[10:11], v[120:121]
	v_cvt_pk_bf16_f32 v123, v132, v123
	global_store_dwordx2 v[126:127], v[122:123], off offset:2560
	v_pk_fma_f32 v[128:129], v[6:7], v[128:129], v[130:131]
	v_lshlrev_b32_e32 v122, 16, v112
; DI float bf2f(unsigned h) { return __uint_as_float(h << 16); }
; DI unsigned pk2(float lo, float hi) { return pg8::cvt_pk_bf16(lo, hi); }
; DI float siluf(float v) { return v * __builtin_amdgcn_rcpf(1.f + __expf(-v)); }
; DI void prep_unit(const Params& P, int layer, int b, int c, char* lds, int tid) {
;     ...
; #pragma unroll
;             for (int li = 0; li < 16; ++li) { const int R = R0 + l0 + li;
;                 const f32x4 x0 = (f32x4){bf2f(xin[li].x & 0xffffu), bf2f(xin[li].x >> 16), bf2f(xin[li].y & 0xffffu), bf2f(xin[li].y >> 16)};
;                 f32x4 y = xw0 * xh2 + xw1 * xh1 + xw2 * xh0 + xw3 * x0 + xb;
;                 xh2 = xh1; xh1 = xh0; xh0 = x0;
;                 y.x = siluf(y.x); y.y = siluf(y.y); y.z = siluf(y.z); y.w = siluf(y.w);
;                 u32x2 w; w.x = pk2(y.x, y.y); w.y = pk2(y.z, y.w); *(u32x2*)(SSDB + (size_t)R * 768 + co) = w; }
	v_and_b32_e32 v123, 0xffff0000, v112
	v_pk_fma_f32 v[128:129], v[14:15], v[124:125], v[128:129]
	v_pk_mul_f32 v[126:127], v[12:13], v[118:119]
	v_pk_fma_f32 v[128:129], v[18:19], v[122:123], v[128:129]
	v_pk_fma_f32 v[126:127], v[8:9], v[136:137], v[126:127]
	v_pk_add_f32 v[128:129], v[2:3], v[128:129]
	v_lshlrev_b32_e32 v112, 16, v113
	v_mul_f32_e32 v130, 0xbfb8aa3b, v128
	v_exp_f32_e32 v130, v130
	v_and_b32_e32 v113, 0xffff0000, v113
	v_pk_fma_f32 v[126:127], v[16:17], v[114:115], v[126:127]
	v_pk_mul_f32 v[132:133], v[10:11], v[124:125]
	v_add_f32_e32 v130, 1.0, v130
	v_rcp_f32_e32 v130, v130
	v_pk_fma_f32 v[126:127], v[20:21], v[112:113], v[126:127]
	v_pk_fma_f32 v[120:121], v[6:7], v[120:121], v[132:133]
	v_pk_add_f32 v[126:127], v[4:5], v[126:127]
	v_mul_f32_e32 v128, v128, v130
	v_mul_f32_e32 v130, 0xbfb8aa3b, v129
	v_exp_f32_e32 v130, v130
	v_pk_fma_f32 v[120:121], v[14:15], v[122:123], v[120:121]
	v_add_f32_e32 v130, 1.0, v130
	v_rcp_f32_e32 v130, v130
	s_nop 0
	v_mul_f32_e32 v129, v129, v130
	v_mul_f32_e32 v130, 0xbfb8aa3b, v126
	v_exp_f32_e32 v130, v130
	s_nop 0
	v_add_f32_e32 v130, 1.0, v130
	v_rcp_f32_e32 v130, v130
	s_nop 0
	v_mul_f32_e32 v130, v126, v130
	v_mul_f32_e32 v126, 0xbfb8aa3b, v127
	v_exp_f32_e32 v126, v126
	s_nop 0
	v_add_f32_e32 v126, 1.0, v126
	v_rcp_f32_e32 v126, v126
	s_nop 0
	v_mul_f32_e32 v127, v127, v126
	v_cvt_pk_bf16_f32 v126, v128, v129
	v_add_co_u32_e32 v128, vcc, s2, v116
	v_cvt_pk_bf16_f32 v127, v130, v127
	v_pk_mul_f32 v[130:131], v[12:13], v[114:115]
	s_nop 0
	v_addc_co_u32_e32 v129, vcc, 0, v117, vcc
	global_store_dwordx2 v[128:129], v[126:127], off
	v_lshlrev_b32_e32 v126, 16, v110
	v_and_b32_e32 v127, 0xffff0000, v110
	v_pk_fma_f32 v[120:121], v[18:19], v[126:127], v[120:121]
	v_pk_fma_f32 v[118:119], v[8:9], v[118:119], v[130:131]
	v_pk_add_f32 v[120:121], v[2:3], v[120:121]
	v_lshlrev_b32_e32 v110, 16, v111
	v_mul_f32_e32 v130, 0xbfb8aa3b, v120
	v_exp_f32_e32 v130, v130
	v_and_b32_e32 v111, 0xffff0000, v111
	v_pk_fma_f32 v[118:119], v[16:17], v[112:113], v[118:119]
	s_mov_b32 s2, 0x1ba04000
	v_add_f32_e32 v130, 1.0, v130
	v_rcp_f32_e32 v130, v130
	v_pk_fma_f32 v[118:119], v[20:21], v[110:111], v[118:119]
	v_mul_f32_e32 v120, v120, v130
	v_mul_f32_e32 v130, 0xbfb8aa3b, v121
	v_exp_f32_e32 v130, v130
	v_pk_add_f32 v[118:119], v[4:5], v[118:119]
	v_add_f32_e32 v130, 1.0, v130
	v_rcp_f32_e32 v130, v130
	s_nop 0
	v_mul_f32_e32 v121, v121, v130
	v_mul_f32_e32 v130, 0xbfb8aa3b, v118
	v_exp_f32_e32 v130, v130
	s_nop 0
	v_add_f32_e32 v130, 1.0, v130
	v_rcp_f32_e32 v130, v130
	s_nop 0
	v_mul_f32_e32 v130, v118, v130
	v_mul_f32_e32 v118, 0xbfb8aa3b, v119
	v_exp_f32_e32 v118, v118
	s_nop 0
	v_add_f32_e32 v118, 1.0, v118
	v_rcp_f32_e32 v118, v118
	s_nop 0
	v_mul_f32_e32 v119, v119, v118
	v_cvt_pk_bf16_f32 v118, v120, v121
	v_cvt_pk_bf16_f32 v119, v130, v119
	v_pk_mul_f32 v[130:131], v[10:11], v[122:123]
	v_pk_mul_f32 v[120:121], v[12:13], v[112:113]
	v_pk_fma_f32 v[124:125], v[6:7], v[124:125], v[130:131]
	global_store_dwordx2 v[128:129], v[118:119], off offset:1536
	v_lshlrev_b32_e32 v118, 16, v108
	v_and_b32_e32 v119, 0xffff0000, v108
	v_pk_fma_f32 v[114:115], v[8:9], v[114:115], v[120:121]
	v_pk_fma_f32 v[120:121], v[14:15], v[126:127], v[124:125]
	v_lshlrev_b32_e32 v108, 16, v109
	v_pk_fma_f32 v[120:121], v[18:19], v[118:119], v[120:121]
	v_and_b32_e32 v109, 0xffff0000, v109
	v_pk_add_f32 v[120:121], v[2:3], v[120:121]
	v_pk_fma_f32 v[114:115], v[16:17], v[110:111], v[114:115]
	v_mul_f32_e32 v124, 0xbfb8aa3b, v120
	v_exp_f32_e32 v124, v124
	v_pk_fma_f32 v[114:115], v[20:21], v[108:109], v[114:115]
	v_add_f32_e32 v124, 1.0, v124
	v_rcp_f32_e32 v124, v124
	v_pk_add_f32 v[114:115], v[4:5], v[114:115]
	v_mul_f32_e32 v120, v120, v124
	v_mul_f32_e32 v124, 0xbfb8aa3b, v121
	v_exp_f32_e32 v124, v124
	s_nop 0
	v_add_f32_e32 v124, 1.0, v124
	v_rcp_f32_e32 v124, v124
	s_nop 0
	v_mul_f32_e32 v121, v121, v124
	v_mul_f32_e32 v124, 0xbfb8aa3b, v114
	v_exp_f32_e32 v124, v124
	s_nop 0
	v_add_f32_e32 v124, 1.0, v124
	v_rcp_f32_e32 v124, v124
	s_nop 0
	v_mul_f32_e32 v124, v114, v124
	v_mul_f32_e32 v114, 0xbfb8aa3b, v115
	v_exp_f32_e32 v114, v114
	s_nop 0
	v_add_f32_e32 v114, 1.0, v114
	v_rcp_f32_e32 v114, v114
	s_nop 0
	v_mul_f32_e32 v115, v115, v114
	v_cvt_pk_bf16_f32 v114, v120, v121
	v_cvt_pk_bf16_f32 v115, v124, v115
	v_pk_mul_f32 v[124:125], v[10:11], v[126:127]
	v_pk_mul_f32 v[120:121], v[12:13], v[110:111]
	v_pk_fma_f32 v[122:123], v[6:7], v[122:123], v[124:125]
	global_store_dwordx2 v[128:129], v[114:115], off offset:3072
	v_lshlrev_b32_e32 v114, 16, v106
	v_and_b32_e32 v115, 0xffff0000, v106
	v_pk_fma_f32 v[112:113], v[8:9], v[112:113], v[120:121]
	v_pk_fma_f32 v[120:121], v[14:15], v[118:119], v[122:123]
	v_lshlrev_b32_e32 v106, 16, v107
	v_pk_fma_f32 v[120:121], v[18:19], v[114:115], v[120:121]
	v_and_b32_e32 v107, 0xffff0000, v107
	v_pk_add_f32 v[120:121], v[2:3], v[120:121]
	v_pk_fma_f32 v[112:113], v[16:17], v[108:109], v[112:113]
	v_mul_f32_e32 v122, 0xbfb8aa3b, v120
	v_exp_f32_e32 v122, v122
	v_pk_fma_f32 v[112:113], v[20:21], v[106:107], v[112:113]
	v_pk_mul_f32 v[124:125], v[10:11], v[118:119]
	v_pk_add_f32 v[112:113], v[4:5], v[112:113]
	v_add_f32_e32 v122, 1.0, v122
	v_rcp_f32_e32 v122, v122
	v_pk_fma_f32 v[124:125], v[6:7], v[126:127], v[124:125]
	v_mul_f32_e32 v120, v120, v122
	v_mul_f32_e32 v122, 0xbfb8aa3b, v121
	v_exp_f32_e32 v122, v122
	s_nop 0
	v_add_f32_e32 v122, 1.0, v122
	v_rcp_f32_e32 v122, v122
	s_nop 0
	v_mul_f32_e32 v121, v121, v122
	v_mul_f32_e32 v122, 0xbfb8aa3b, v112
	v_exp_f32_e32 v122, v122
	s_nop 0
	v_add_f32_e32 v122, 1.0, v122
	v_rcp_f32_e32 v122, v122
	s_nop 0
; DI float bf2f(unsigned h) { return __uint_as_float(h << 16); }
; DI unsigned pk2(float lo, float hi) { return pg8::cvt_pk_bf16(lo, hi); }
; DI float siluf(float v) { return v * __builtin_amdgcn_rcpf(1.f + __expf(-v)); }
; DI void prep_unit(const Params& P, int layer, int b, int c, char* lds, int tid) {
;     ...
; #pragma unroll
;             for (int li = 0; li < 16; ++li) { const int R = R0 + l0 + li;
;                 const f32x4 x0 = (f32x4){bf2f(xin[li].x & 0xffffu), bf2f(xin[li].x >> 16), bf2f(xin[li].y & 0xffffu), bf2f(xin[li].y >> 16)};
;                 f32x4 y = xw0 * xh2 + xw1 * xh1 + xw2 * xh0 + xw3 * x0 + xb;
;                 xh2 = xh1; xh1 = xh0; xh0 = x0;
;                 y.x = siluf(y.x); y.y = siluf(y.y); y.z = siluf(y.z); y.w = siluf(y.w);
;                 u32x2 w; w.x = pk2(y.x, y.y); w.y = pk2(y.z, y.w); *(u32x2*)(SSDB + (size_t)R * 768 + co) = w; }
	v_mul_f32_e32 v122, v112, v122
	v_mul_f32_e32 v112, 0xbfb8aa3b, v113
	v_exp_f32_e32 v112, v112
	s_nop 0
	v_add_f32_e32 v112, 1.0, v112
	v_rcp_f32_e32 v112, v112
	s_nop 0
	v_mul_f32_e32 v113, v113, v112
	v_cvt_pk_bf16_f32 v112, v120, v121
	v_add_co_u32_e32 v120, vcc, s2, v116
	v_cvt_pk_bf16_f32 v113, v122, v113
	v_pk_mul_f32 v[122:123], v[12:13], v[108:109]
	s_nop 0
	v_addc_co_u32_e32 v121, vcc, 0, v117, vcc
	global_store_dwordx2 v[120:121], v[112:113], off offset:512
	v_lshlrev_b32_e32 v112, 16, v104
	v_and_b32_e32 v113, 0xffff0000, v104
	v_pk_fma_f32 v[110:111], v[8:9], v[110:111], v[122:123]
	v_pk_fma_f32 v[122:123], v[14:15], v[114:115], v[124:125]
	v_lshlrev_b32_e32 v104, 16, v105
	v_pk_fma_f32 v[122:123], v[18:19], v[112:113], v[122:123]
	v_and_b32_e32 v105, 0xffff0000, v105
	v_pk_add_f32 v[122:123], v[2:3], v[122:123]
	v_pk_fma_f32 v[110:111], v[16:17], v[106:107], v[110:111]
	v_mul_f32_e32 v124, 0xbfb8aa3b, v122
	v_exp_f32_e32 v124, v124
	v_pk_fma_f32 v[110:111], v[20:21], v[104:105], v[110:111]
	s_mov_b32 s2, 0x1ba05000
	v_pk_add_f32 v[110:111], v[4:5], v[110:111]
	v_add_f32_e32 v124, 1.0, v124
	v_rcp_f32_e32 v124, v124
	s_nop 0
	v_mul_f32_e32 v122, v122, v124
	v_mul_f32_e32 v124, 0xbfb8aa3b, v123
	v_exp_f32_e32 v124, v124
	s_nop 0
	v_add_f32_e32 v124, 1.0, v124
	v_rcp_f32_e32 v124, v124
	s_nop 0
	v_mul_f32_e32 v123, v123, v124
	v_mul_f32_e32 v124, 0xbfb8aa3b, v110
	v_exp_f32_e32 v124, v124
	s_nop 0
	v_add_f32_e32 v124, 1.0, v124
	v_rcp_f32_e32 v124, v124
	s_nop 0
	v_mul_f32_e32 v124, v110, v124
	v_mul_f32_e32 v110, 0xbfb8aa3b, v111
	v_exp_f32_e32 v110, v110
	s_nop 0
	v_add_f32_e32 v110, 1.0, v110
	v_rcp_f32_e32 v110, v110
	s_nop 0
	v_mul_f32_e32 v111, v111, v110
	v_cvt_pk_bf16_f32 v110, v122, v123
	v_cvt_pk_bf16_f32 v111, v124, v111
	v_pk_mul_f32 v[124:125], v[10:11], v[114:115]
	global_store_dwordx2 v[120:121], v[110:111], off offset:2048
	v_pk_fma_f32 v[118:119], v[6:7], v[118:119], v[124:125]
	s_waitcnt vmcnt(15)
	v_lshlrev_b32_e32 v110, 16, v102
	v_and_b32_e32 v111, 0xffff0000, v102
	v_pk_fma_f32 v[118:119], v[14:15], v[112:113], v[118:119]
	v_pk_mul_f32 v[122:123], v[12:13], v[106:107]
	v_pk_fma_f32 v[118:119], v[18:19], v[110:111], v[118:119]
	v_pk_fma_f32 v[108:109], v[8:9], v[108:109], v[122:123]
	v_pk_add_f32 v[118:119], v[2:3], v[118:119]
	v_lshlrev_b32_e32 v102, 16, v103
	v_mul_f32_e32 v122, 0xbfb8aa3b, v118
	v_exp_f32_e32 v122, v122
	v_and_b32_e32 v103, 0xffff0000, v103
	v_pk_fma_f32 v[108:109], v[16:17], v[104:105], v[108:109]
	v_add_f32_e32 v122, 1.0, v122
	v_rcp_f32_e32 v122, v122
	v_pk_fma_f32 v[108:109], v[20:21], v[102:103], v[108:109]
	v_mul_f32_e32 v118, v118, v122
	v_mul_f32_e32 v122, 0xbfb8aa3b, v119
	v_exp_f32_e32 v122, v122
	v_pk_add_f32 v[108:109], v[4:5], v[108:109]
	v_add_f32_e32 v122, 1.0, v122
	v_rcp_f32_e32 v122, v122
	s_nop 0
	v_mul_f32_e32 v119, v119, v122
	v_mul_f32_e32 v122, 0xbfb8aa3b, v108
	v_exp_f32_e32 v122, v122
	s_nop 0
	v_add_f32_e32 v122, 1.0, v122
	v_rcp_f32_e32 v122, v122
	s_nop 0
	v_mul_f32_e32 v122, v108, v122
	v_mul_f32_e32 v108, 0xbfb8aa3b, v109
	v_exp_f32_e32 v108, v108
	s_nop 0
	v_add_f32_e32 v108, 1.0, v108
	v_rcp_f32_e32 v108, v108
	s_nop 0
	v_mul_f32_e32 v109, v109, v108
	v_cvt_pk_bf16_f32 v108, v118, v119
	v_cvt_pk_bf16_f32 v109, v122, v109
	global_store_dwordx2 v[120:121], v[108:109], off offset:3584
	v_pk_mul_f32 v[120:121], v[10:11], v[112:113]
	s_waitcnt vmcnt(15)
	v_lshlrev_b32_e32 v108, 16, v100
	v_pk_fma_f32 v[114:115], v[6:7], v[114:115], v[120:121]
	v_and_b32_e32 v109, 0xffff0000, v100
	v_pk_fma_f32 v[114:115], v[14:15], v[110:111], v[114:115]
	v_pk_mul_f32 v[118:119], v[12:13], v[104:105]
	v_pk_fma_f32 v[114:115], v[18:19], v[108:109], v[114:115]
	v_pk_fma_f32 v[106:107], v[8:9], v[106:107], v[118:119]
	v_pk_add_f32 v[114:115], v[2:3], v[114:115]
	v_lshlrev_b32_e32 v100, 16, v101
	v_mul_f32_e32 v118, 0xbfb8aa3b, v114
	v_exp_f32_e32 v118, v118
	v_and_b32_e32 v101, 0xffff0000, v101
	v_pk_fma_f32 v[106:107], v[16:17], v[102:103], v[106:107]
	v_pk_mul_f32 v[10:11], v[10:11], v[110:111]
	v_add_f32_e32 v118, 1.0, v118
	v_rcp_f32_e32 v118, v118
	v_pk_fma_f32 v[106:107], v[20:21], v[100:101], v[106:107]
	v_pk_fma_f32 v[6:7], v[6:7], v[112:113], v[10:11]
	v_pk_add_f32 v[106:107], v[4:5], v[106:107]
	v_mul_f32_e32 v114, v114, v118
	v_mul_f32_e32 v118, 0xbfb8aa3b, v115
	v_exp_f32_e32 v118, v118
	v_pk_fma_f32 v[6:7], v[14:15], v[108:109], v[6:7]
	v_pk_mul_f32 v[12:13], v[12:13], v[102:103]
	v_add_f32_e32 v118, 1.0, v118
	v_rcp_f32_e32 v118, v118
	v_pk_fma_f32 v[8:9], v[8:9], v[104:105], v[12:13]
	v_mul_f32_e32 v115, v115, v118
	v_mul_f32_e32 v118, 0xbfb8aa3b, v106
	v_exp_f32_e32 v118, v118
	v_pk_fma_f32 v[8:9], v[16:17], v[100:101], v[8:9]
	v_add_f32_e32 v118, 1.0, v118
	v_rcp_f32_e32 v118, v118
	s_nop 0
	v_mul_f32_e32 v118, v106, v118
	v_mul_f32_e32 v106, 0xbfb8aa3b, v107
	v_exp_f32_e32 v106, v106
	s_nop 0
	v_add_f32_e32 v106, 1.0, v106
	v_rcp_f32_e32 v106, v106
	s_nop 0
	v_mul_f32_e32 v107, v107, v106
	v_cvt_pk_bf16_f32 v106, v114, v115
	v_add_co_u32_e32 v114, vcc, s2, v116
	v_cvt_pk_bf16_f32 v107, v118, v107
	s_nop 1
	v_addc_co_u32_e32 v115, vcc, 0, v117, vcc
	global_store_dwordx2 v[114:115], v[106:107], off offset:1024
	s_waitcnt vmcnt(15)
	v_lshlrev_b32_e32 v106, 16, v98
	v_and_b32_e32 v107, 0xffff0000, v98
	v_pk_fma_f32 v[6:7], v[18:19], v[106:107], v[6:7]
	v_lshlrev_b32_e32 v98, 16, v99
	v_pk_add_f32 v[2:3], v[2:3], v[6:7]
	v_and_b32_e32 v99, 0xffff0000, v99
	v_mul_f32_e32 v6, 0xbfb8aa3b, v2
	v_exp_f32_e32 v6, v6
	v_pk_fma_f32 v[8:9], v[20:21], v[98:99], v[8:9]
	v_add_f32_e32 v6, 1.0, v6
	v_rcp_f32_e32 v6, v6
	v_pk_add_f32 v[4:5], v[4:5], v[8:9]
	v_mul_f32_e32 v2, v2, v6
	v_mul_f32_e32 v6, 0xbfb8aa3b, v3
	v_exp_f32_e32 v6, v6
	s_nop 0
	v_add_f32_e32 v6, 1.0, v6
	v_rcp_f32_e32 v6, v6
	s_nop 0
	v_mul_f32_e32 v3, v3, v6
	v_mul_f32_e32 v6, 0xbfb8aa3b, v4
	v_exp_f32_e32 v6, v6
	v_cvt_pk_bf16_f32 v2, v2, v3
	s_nop 0
	v_add_f32_e32 v6, 1.0, v6
	v_rcp_f32_e32 v6, v6
	s_nop 0
	v_mul_f32_e32 v4, v4, v6
	v_mul_f32_e32 v6, 0xbfb8aa3b, v5
	v_exp_f32_e32 v6, v6
	s_nop 0
	v_add_f32_e32 v6, 1.0, v6
	v_rcp_f32_e32 v6, v6
	s_nop 0
	v_mul_f32_e32 v5, v5, v6
	v_cvt_pk_bf16_f32 v3, v4, v5
	global_store_dwordx2 v[114:115], v[2:3], off offset:2560
	s_cbranch_scc0 .LBB0_193
; DI void chunk_cumsum(float* acs, const float* dtl, const float* a_log, int wave, int lane) {
;     if (wave < 4) { const float A = -expf(a_log[wave]); const float a0 = dtl[wave * CH + 2 * lane] * A, a1 = dtl[wave * CH + 2 * lane + 1] * A; float x = a0 + a1;
; #pragma unroll
;         for (int o = 1; o < 64; o <<= 1) { const float t = __shfl_up(x, o); if (lane >= o) x += t; }
;         acs[wave * CH + 2 * lane] = x - a1; acs[wave * CH + 2 * lane + 1] = x; }
; DI void prep_unit(const Params& P, int layer, int b, int c, char* lds, int tid) {
;     ...
;     asm volatile("s_waitcnt vmcnt(0)" ::: "memory"); __syncthreads();
;     chunk_cumsum(acs, dtl, alog, wave, lane);
	s_waitcnt vmcnt(0)
	s_waitcnt lgkmcnt(0)
	s_barrier
	s_and_saveexec_b64 s[38:39], s[42:43]
	s_cbranch_execz .LBB0_196
	global_load_dword v2, v[36:37], off
	v_add_u32_e32 v6, -1, v207
	s_waitcnt vmcnt(0)
	v_mul_f32_e32 v3, 0x3fb8aa3b, v2
	v_rndne_f32_e32 v4, v3
	v_sub_f32_e32 v5, v3, v4
	v_fma_f32 v3, v2, s11, -v3
	v_fmac_f32_e32 v3, 0x32a5705f, v2
	v_add_f32_e32 v3, v5, v3
	v_exp_f32_e32 v3, v3
	v_cvt_i32_f32_e32 v4, v4
	v_cmp_ngt_f32_e32 vcc, s0, v2
	v_and_b32_e32 v5, 64, v207
	v_ldexp_f32 v3, v3, v4
	v_cndmask_b32_e32 v3, 0, v3, vcc
	v_cmp_nlt_f32_e32 vcc, s1, v2
	s_nop 1
	v_cndmask_b32_e32 v4, v206, v3, vcc
	ds_read_b64 v[2:3], v33
	v_cmp_lt_i32_e32 vcc, v6, v5
	s_waitcnt lgkmcnt(0)
	v_mul_f32_e32 v2, v4, v2
	v_cndmask_b32_e32 v6, v6, v207, vcc
	v_fma_f32 v2, v3, -v4, -v2
	v_lshlrev_b32_e32 v6, 2, v6
	ds_bpermute_b32 v6, v6, v2
	s_waitcnt lgkmcnt(0)
	v_add_f32_e32 v6, v2, v6
	v_cndmask_b32_e64 v2, v6, v2, s[22:23]
	v_add_u32_e32 v6, -2, v207
	v_cmp_lt_i32_e32 vcc, v6, v5
	s_nop 1
	v_cndmask_b32_e32 v6, v6, v207, vcc
	v_lshlrev_b32_e32 v6, 2, v6
	ds_bpermute_b32 v6, v6, v2
	s_waitcnt lgkmcnt(0)
	v_add_f32_e32 v6, v2, v6
	v_cndmask_b32_e64 v2, v6, v2, s[46:47]
	v_add_u32_e32 v6, -4, v207
	v_cmp_lt_i32_e32 vcc, v6, v5
	s_nop 1
	v_cndmask_b32_e32 v6, v6, v207, vcc
	v_lshlrev_b32_e32 v6, 2, v6
	ds_bpermute_b32 v6, v6, v2
	s_waitcnt lgkmcnt(0)
	v_add_f32_e32 v6, v2, v6
	v_cndmask_b32_e64 v2, v6, v2, s[40:41]
	v_add_u32_e32 v6, -8, v207
	v_cmp_lt_i32_e32 vcc, v6, v5
	s_nop 1
	v_cndmask_b32_e32 v6, v6, v207, vcc
	v_lshlrev_b32_e32 v6, 2, v6
	ds_bpermute_b32 v6, v6, v2
	s_waitcnt lgkmcnt(0)
	v_add_f32_e32 v6, v2, v6
	v_cndmask_b32_e64 v2, v6, v2, s[48:49]
	v_add_u32_e32 v6, -16, v207
	v_cmp_lt_i32_e32 vcc, v6, v5
	s_nop 1
	v_cndmask_b32_e32 v6, v6, v207, vcc
	v_lshlrev_b32_e32 v6, 2, v6
	ds_bpermute_b32 v6, v6, v2
	s_waitcnt lgkmcnt(0)
	v_add_f32_e32 v6, v2, v6
	v_cndmask_b32_e64 v2, v6, v2, s[50:51]
	v_subrev_u32_e32 v6, 32, v207
	v_cmp_lt_i32_e32 vcc, v6, v5
	s_nop 1
	v_cndmask_b32_e32 v5, v6, v207, vcc
	v_lshlrev_b32_e32 v5, 2, v5
	ds_bpermute_b32 v5, v5, v2
	s_waitcnt lgkmcnt(0)
	v_add_f32_e32 v5, v2, v5
	v_cndmask_b32_e64 v5, v5, v2, s[52:53]
	v_fma_f32 v4, v3, v4, v5
	ds_write_b64 v158, v[4:5]
